# P5: per-segment s_setprio flips removed, one static s_setprio 1 for waves 4-7 for the phase; with barrier edits + P2 plain stores
# speedup vs baseline: 1.0039x; 1.0039x over previous
; #define LAS __attribute__((address_space(3)))
;     __device__ __forceinline__ void prefetch(const pg8::Unit& u, int buf, int wid, int lane) const {
;         if (wid < 6) {
;             const int gpm = pm0 + u.pm, b = batch_of_tile(gpm);
;             const float* src = wid == 0 ? rss2 + gpm * 256 : wid == 1 ? c2 + b * FF2 + u.pn * 256 : wid < 5 ? convp + (wid - 2) * FF2 + u.pn * 256 : cbp + u.pn * 256;
;             __builtin_amdgcn_global_load_lds((const unsigned*)(src + 4 * lane), (LAS unsigned*)(X + 2048 + buf * 1536 + wid * 256), 16, 0, 0);
.LBB0_510:
	s_or_b64 exec, exec, s[0:1]
	s_add_u32 s22, s62, 0x1b00000
	s_addc_u32 s23, s63, 0
	v_mov_b32_e32 v3, v0
	s_waitcnt lgkmcnt(0)
	s_barrier
	s_cmpk_lt_i32 s97, 0x160
	s_nop 0
	v_readfirstlane_b32 s6, v3
	s_cbranch_scc0 .LBB0_562
	s_nop 3
	s_cmp_lt_u32 s6, 0x100
	s_cbranch_scc1 .Lp5prio_skip
	s_setprio 1
.Lp5prio_skip:
	s_mul_hi_i32 s0, s97, 0x2e8ba2e9
	s_lshr_b32 s1, s0, 31
	s_ashr_i32 s0, s0, 5
	s_add_i32 s0, s0, s1
	s_mul_i32 s1, s0, 0xb0
	s_sub_i32 s1, s97, s1
	s_lshl_b32 s0, s0, 3
	s_add_i32 s0, s0, s77
	s_and_b32 s2, s1, 7
	s_ashr_i32 s11, s6, 6
	s_or_b32 s54, s0, s2
	s_ashr_i32 s52, s1, 3
	s_lshl_b32 s13, s11, 10
	s_cmp_lt_i32 s11, 6
	v_and_b32_e32 v2, 63, v3
	s_cselect_b64 s[24:25], -1, 0
	s_cmp_gt_i32 s11, 5
	s_mul_i32 s7, s11, 0x1600
	s_cbranch_scc1 .LBB0_524
	s_add_i32 s8, s54, s70
	s_cmp_lt_i32 s11, 1
	s_cbranch_scc1 .LBB0_520
	s_cmp_gt_i32 s11, 4
	s_mov_b64 s[0:1], -1
	s_cbranch_scc0 .LBB0_515
	s_mov_b64 s[0:1], 0

; #define PG8_WAIT_V(n) asm volatile("s_waitcnt vmcnt(" #n ")" ::: "memory")
; #define PG8_BAR __builtin_amdgcn_s_barrier()
; template <class Epi, class Sched, bool ALIGN_EPI = false, bool SP2 = false>
; __device__ __forceinline__ void gemm_phase(PG8_LAS unsigned char* lds, const Gemm g, const Sched& S, const Epi& E, volatile PG8_LAS unsigned* sw = nullptr) {
;     ...
;     PG8_WAIT_V(0);
;     if constexpr (!ALIGN_EPI) { if (wr == 0) PG8_BAR; }
;     PG8_BAR;
; __device__ __forceinline__ void xcd_barrier(const XcdBarrier& b) {
;     asm volatile("s_waitcnt vmcnt(0)" ::: "memory");
;     __syncthreads();
;     if (threadIdx.x == 0) {
;         unsigned* bar = b.bar;
;         __builtin_amdgcn_s_waitcnt(0);
;         unsigned nloc = b.st[0], nx = b.st[1];
;         if (nloc == 0u) { xcd_barrier_complete(bar, b.x, b.gsize, nloc, nx); b.st[0] = nloc; b.st[1] = nx; }
.LBB0_562:
	s_setprio 0
	s_waitcnt vmcnt(0)
	s_waitcnt vmcnt(0) lgkmcnt(0)
	s_barrier
	s_and_saveexec_b64 s[0:1], s[90:91]
	v_readlane_b32 s42, v250, 18
	s_xor_b64 s[0:1], exec, s[0:1]
	v_readlane_b32 s43, v250, 19
	s_cbranch_execz .LBB0_615
	s_add_i32 s2, 0, 0x26170
	v_mov_b32_e32 v1, s2
	s_waitcnt vmcnt(0) expcnt(0) lgkmcnt(0)
	ds_read_b32 v3, v1
	s_add_i32 s2, 0, 0x26174
	v_mov_b32_e32 v1, s2
	ds_read_b32 v1, v1
	s_waitcnt lgkmcnt(1)
	v_cmp_ne_u32_e32 vcc, 0, v3
	s_cbranch_vccnz .LBB0_578
	s_add_u32 s2, s34, 0x1000
	s_addc_u32 s3, s35, 0
	s_add_u32 s4, s34, 0x1100
	s_addc_u32 s5, s35, 0
	s_add_u32 s6, s34, 0x1200
	s_addc_u32 s7, s35, 0
	s_add_u32 s8, s34, 0x1300
	s_addc_u32 s9, s35, 0
	s_mov_b32 s11, 1
	v_mov_b32_e32 v17, 0
	s_branch .LBB0_566
